# GEMM unit-boundary counted waits: the first two LDS-DMA waits of each unit no longer retire the previous unit's epilogue stores (vmcnt 8+S / 6+S in the peeled first iteration; phase prologue drained o
# speedup vs baseline: 1.0007x; 1.0007x over previous
.LBB0_55:
	s_mov_b64 s[14:15], 0x80
	s_bfe_u32 s6, s76, 0x20006
	s_add_i32 m0, s34, 0x18000
	v_lshl_add_u64 v[6:7], v[6:7], 0, s[14:15]
	s_lshl_b32 s7, s6, 12
	s_waitcnt vmcnt(2)
	s_barrier
	global_load_lds_dwordx4 v[6:7], off
	v_lshl_add_u64 v[4:5], v[4:5], 0, s[14:15]
	s_add_i32 m0, s34, 0x1a000
	s_add_i32 s42, s34, 0x8000
	s_add_i32 s43, s34, 0xa000
	global_load_lds_dwordx4 v[4:5], off
	v_lshl_add_u64 v[0:1], v[0:1], 0, s[14:15]
	s_mov_b32 m0, s42
	s_add_u32 s4, s0, 0x40080
	global_load_lds_dwordx4 v[0:1], off
	v_lshl_add_u64 v[0:1], v[2:3], 0, s[14:15]
	s_mov_b32 m0, s43
	s_addc_u32 s5, s1, 0
	global_load_lds_dwordx4 v[0:1], off
	s_add_i32 m0, s34, 0x1c000
	v_lshl_add_u64 v[0:1], s[4:5], 0, v[160:161]
	global_load_lds_dwordx4 v[0:1], off
	v_lshl_add_u64 v[0:1], s[4:5], 0, v[162:163]
	s_add_i32 m0, s34, 0x1e000
	v_and_b32_e32 v2, 48, v8
	global_load_lds_dwordx4 v[0:1], off
	v_and_b32_e32 v0, 15, v8
	v_or_b32_e32 v1, s91, v0
	v_lshlrev_b32_e32 v3, 6, v1
	s_movk_i32 s4, 0x3c0
	v_and_or_b32 v3, v3, s4, v2
	v_lshlrev_b32_e32 v1, 2, v1
	v_lshl_or_b32 v0, v0, 6, v2
	v_lshlrev_b32_e32 v2, 2, v8
	s_cmpk_lt_u32 s76, 0x100
	v_and_b32_e32 v1, 32, v1
	v_readlane_b32 s4, v253, 38
	v_and_b32_e32 v2, 32, v2
	s_cselect_b64 s[16:17], -1, 0
	s_bitcmp0_b32 s76, 6
	v_bitop3_b32 v1, v3, s4, v1 bitop3:0xde
	v_bitop3_b32 v176, v0, s7, v2 bitop3:0xde
	s_cselect_b64 s[18:19], -1, 0
	s_lshl_b32 s4, s6, 6
	v_add_u32_e32 v0, 64, v246
	s_add_u32 s45, s96, s4
	v_cmp_lt_i32_e32 vcc, v241, v0
	s_waitcnt vmcnt(6)
	s_addc_u32 s46, s97, 0
	s_add_u32 s47, s66, 0x19400080
	v_cndmask_b32_e32 v0, v174, v241, vcc
	v_lshlrev_b32_e32 v177, 2, v0
	v_add_u32_e32 v0, 0, v176
	s_mov_b32 s44, 0x8000
	s_addc_u32 s48, s67, 0
	v_add_u32_e32 v178, 0x10000, v0
	v_add_u32_e32 v179, 0x14000, v0
	v_add_u32_e32 v180, 0, v1
	s_add_i32 s49, s34, 0xc000
	s_add_i32 s50, s34, 0xe000
	v_mov_b32_e32 v181, 0x1fcf
	v_mov_b32_e32 v182, 0xfcf
	v_mov_b32_e32 v183, 0x1fdf
	v_mov_b32_e32 v184, 0xfdf
	v_mov_b32_e32 v185, 0x1fef
	v_mov_b32_e32 v186, 0xfef
	v_mov_b32_e32 v187, 0x1fff
	v_mov_b32_e32 v188, 0xfff
	s_mov_b32 s51, 0
	s_barrier
	v_add_u32_e32 v247, s33, v174
	v_bfe_u32 v248, v247, 6, 1
	v_and_b32_e32 v249, 3, v247
	v_bfe_u32 v250, v247, 5, 1
	v_lshlrev_b32_e32 v249, 4, v249
	v_lshlrev_b32_e32 v250, 5, v250
	v_xor_b32_e32 v249, v249, v250
	v_lshl_add_u32 v248, v248, 6, v249
	v_lshrrev_b32_e32 v249, 7, v247
	v_bfe_u32 v247, v247, 2, 4
	v_lshl_add_u32 v247, v249, 4, v247
	v_lshl_add_u32 v247, v247, 11, v248
	s_waitcnt vmcnt(0)
	s_branch .LBB0_58

.LBB0_60:
	s_ashr_i32 s21, s20, 31
	s_lshl_b64 s[4:5], s[20:21], 19
	s_add_u32 s24, s66, s4
	s_addc_u32 s25, s67, s5
	s_and_b64 s[4:5], s[22:23], exec
	s_cselect_b32 s21, s25, s1
	s_cselect_b32 s27, s24, s0
	s_lshl_b32 s29, s52, 8
	s_or_b32 s30, s29, 0x80
	s_add_u32 s31, s0, 0x100
	s_addc_u32 s53, s1, 0
	s_mov_b32 s54, -2
	s_mov_b64 s[0:1], 0
	ds_read_b128 v[144:147], v178
	ds_read_b128 v[148:151], v178 offset:1024
	ds_read_b128 v[152:155], v178 offset:2048
	ds_read_b128 v[156:159], v178 offset:3072
	ds_read_b128 v[128:131], v179
	ds_read_b128 v[132:135], v179 offset:1024
	ds_read_b128 v[136:139], v179 offset:2048
	ds_read_b128 v[140:143], v179 offset:3072
	s_cmp_eq_u32 s54, 12
	s_cselect_b64 s[6:7], -1, 0
	s_add_u32 s4, s47, s0
	s_addc_u32 s5, s48, s1
	s_mov_b32 m0, s49
	ds_read_b128 v[190:193], v180
	ds_read_b128 v[194:197], v180 offset:1024
	ds_read_b128 v[198:201], v180 offset:2048
	ds_read_b128 v[202:205], v180 offset:3072
	ds_read_b128 v[206:209], v180 offset:4096
	ds_read_b128 v[210:213], v180 offset:5120
	ds_read_b128 v[214:217], v180 offset:6144
	ds_read_b128 v[218:221], v180 offset:7168
	global_load_lds_dwordx4 v168, s[4:5]
	s_mov_b32 m0, s50
	s_nop 0
	global_load_lds_dwordx4 v170, s[4:5]
	s_waitcnt vmcnt(24)
	s_waitcnt lgkmcnt(0)
	s_barrier
	s_setprio 1
	s_waitcnt lgkmcnt(0)
	v_mfma_f32_16x16x32_bf16 v[124:127], v[144:147], v[190:193], 0
	v_mfma_f32_16x16x32_bf16 v[120:123], v[152:155], v[190:193], 0
	v_mfma_f32_16x16x32_bf16 v[108:111], v[144:147], v[198:201], 0
	v_mfma_f32_16x16x32_bf16 v[104:107], v[152:155], v[198:201], 0
	v_mfma_f32_16x16x32_bf16 v[92:95], v[144:147], v[206:209], 0
	v_mfma_f32_16x16x32_bf16 v[88:91], v[152:155], v[206:209], 0
	v_mfma_f32_16x16x32_bf16 v[76:79], v[144:147], v[214:217], 0
	v_mfma_f32_16x16x32_bf16 v[72:75], v[152:155], v[214:217], 0
	v_mfma_f32_16x16x32_bf16 v[124:127], v[148:151], v[194:197], v[124:127]
	v_mfma_f32_16x16x32_bf16 v[120:123], v[156:159], v[194:197], v[120:123]
	v_mfma_f32_16x16x32_bf16 v[108:111], v[148:151], v[202:205], v[108:111]
	v_mfma_f32_16x16x32_bf16 v[104:107], v[156:159], v[202:205], v[104:107]
	v_mfma_f32_16x16x32_bf16 v[92:95], v[148:151], v[210:213], v[92:95]
	v_mfma_f32_16x16x32_bf16 v[88:91], v[156:159], v[210:213], v[88:91]
	v_mfma_f32_16x16x32_bf16 v[76:79], v[148:151], v[218:221], v[76:79]
	v_mfma_f32_16x16x32_bf16 v[72:75], v[156:159], v[218:221], v[72:75]
	v_mfma_f32_16x16x32_bf16 v[116:119], v[128:131], v[190:193], 0
	v_mfma_f32_16x16x32_bf16 v[112:115], v[136:139], v[190:193], 0
	v_mfma_f32_16x16x32_bf16 v[100:103], v[128:131], v[198:201], 0
	v_mfma_f32_16x16x32_bf16 v[96:99], v[136:139], v[198:201], 0
	v_mfma_f32_16x16x32_bf16 v[84:87], v[128:131], v[206:209], 0
	v_mfma_f32_16x16x32_bf16 v[80:83], v[136:139], v[206:209], 0
	v_mfma_f32_16x16x32_bf16 v[68:71], v[128:131], v[214:217], 0
	v_mfma_f32_16x16x32_bf16 v[64:67], v[136:139], v[214:217], 0
	v_mfma_f32_16x16x32_bf16 v[116:119], v[132:135], v[194:197], v[116:119]
	v_mfma_f32_16x16x32_bf16 v[112:115], v[140:143], v[194:197], v[112:115]
	v_mfma_f32_16x16x32_bf16 v[100:103], v[132:135], v[202:205], v[100:103]
	v_mfma_f32_16x16x32_bf16 v[96:99], v[140:143], v[202:205], v[96:99]
	v_mfma_f32_16x16x32_bf16 v[84:87], v[132:135], v[210:213], v[84:87]
	v_mfma_f32_16x16x32_bf16 v[80:83], v[140:143], v[210:213], v[80:83]
	v_mfma_f32_16x16x32_bf16 v[68:71], v[132:135], v[218:221], v[68:71]
	v_mfma_f32_16x16x32_bf16 v[64:67], v[140:143], v[218:221], v[64:67]
	s_setprio 0
	s_barrier
	s_and_b64 s[4:5], s[22:23], s[6:7]
	s_andn2_b64 vcc, exec, s[4:5]
	s_cbranch_vccnz .Lpk0_LBB0_63
	s_lshl_b32 s57, s29, 11
	s_lshl_b32 s58, s30, 11
	v_add_u32_e32 v164, s57, v247
	v_add_u32_e32 v168, s58, v247
	v_add_u32_e32 v166, 0x20000, v164
	v_add_u32_e32 v170, 0x20000, v168
	s_branch .Lpk0_LBB0_64
.Lpk0_LBB0_63:
.Lpk0_LBB0_64:
	s_add_u32 s4, s0, 0x100
	s_addc_u32 s5, s1, 0
	s_and_b64 s[56:57], s[6:7], exec
	s_cselect_b32 s8, 0, s4
	s_add_u32 s55, s31, s0
	s_addc_u32 s56, s53, s1
	s_and_b64 s[0:1], s[6:7], exec
	s_cselect_b32 s1, s21, s56
	s_cselect_b32 s0, s27, s55
	s_add_u32 s98, s2, s8
	s_addc_u32 s99, s3, s9
	s_mov_b32 m0, s35
	s_add_u32 s6, s0, 0x40000
	ds_read_b128 v[190:193], v180 offset:16384
	ds_read_b128 v[194:197], v180 offset:17408
	ds_read_b128 v[198:201], v180 offset:18432
	ds_read_b128 v[202:205], v180 offset:19456
	ds_read_b128 v[206:209], v180 offset:20480
	ds_read_b128 v[210:213], v180 offset:21504
	ds_read_b128 v[214:217], v180 offset:22528
	ds_read_b128 v[218:221], v180 offset:23552
	global_load_lds_dwordx4 v160, s[0:1]
	s_mov_b32 m0, s36
	s_addc_u32 s7, s1, 0
	global_load_lds_dwordx4 v162, s[0:1]
	s_mov_b32 m0, s37
	s_nop 0
	global_load_lds_dwordx4 v160, s[6:7]
	s_mov_b32 m0, s38
	s_nop 0
	global_load_lds_dwordx4 v162, s[6:7]
	s_waitcnt vmcnt(22)
	s_waitcnt lgkmcnt(0)
	s_barrier
	s_setprio 1
	s_waitcnt lgkmcnt(0)
	v_mfma_f32_16x16x32_bf16 v[60:63], v[144:147], v[190:193], 0
	v_mfma_f32_16x16x32_bf16 v[56:59], v[152:155], v[190:193], 0
	v_mfma_f32_16x16x32_bf16 v[44:47], v[144:147], v[198:201], 0
	v_mfma_f32_16x16x32_bf16 v[40:43], v[152:155], v[198:201], 0
	v_mfma_f32_16x16x32_bf16 v[28:31], v[144:147], v[206:209], 0
	v_mfma_f32_16x16x32_bf16 v[24:27], v[152:155], v[206:209], 0
	v_mfma_f32_16x16x32_bf16 v[12:15], v[144:147], v[214:217], 0
	v_mfma_f32_16x16x32_bf16 v[8:11], v[152:155], v[214:217], 0
	v_mfma_f32_16x16x32_bf16 v[60:63], v[148:151], v[194:197], v[60:63]
	v_mfma_f32_16x16x32_bf16 v[56:59], v[156:159], v[194:197], v[56:59]
	v_mfma_f32_16x16x32_bf16 v[44:47], v[148:151], v[202:205], v[44:47]
	v_mfma_f32_16x16x32_bf16 v[40:43], v[156:159], v[202:205], v[40:43]
	v_mfma_f32_16x16x32_bf16 v[28:31], v[148:151], v[210:213], v[28:31]
	v_mfma_f32_16x16x32_bf16 v[24:27], v[156:159], v[210:213], v[24:27]
	v_mfma_f32_16x16x32_bf16 v[12:15], v[148:151], v[218:221], v[12:15]
	v_mfma_f32_16x16x32_bf16 v[8:11], v[156:159], v[218:221], v[8:11]
	v_mfma_f32_16x16x32_bf16 v[52:55], v[128:131], v[190:193], 0
	v_mfma_f32_16x16x32_bf16 v[48:51], v[136:139], v[190:193], 0
	v_mfma_f32_16x16x32_bf16 v[36:39], v[128:131], v[198:201], 0
	v_mfma_f32_16x16x32_bf16 v[32:35], v[136:139], v[198:201], 0
	v_mfma_f32_16x16x32_bf16 v[20:23], v[128:131], v[206:209], 0
	v_mfma_f32_16x16x32_bf16 v[16:19], v[136:139], v[206:209], 0
	v_mfma_f32_16x16x32_bf16 v[4:7], v[128:131], v[214:217], 0
	v_mfma_f32_16x16x32_bf16 v[0:3], v[136:139], v[214:217], 0
	v_mfma_f32_16x16x32_bf16 v[52:55], v[132:135], v[194:197], v[52:55]
	v_mfma_f32_16x16x32_bf16 v[48:51], v[140:143], v[194:197], v[48:51]
	v_mfma_f32_16x16x32_bf16 v[36:39], v[132:135], v[202:205], v[36:39]
	v_mfma_f32_16x16x32_bf16 v[32:35], v[140:143], v[202:205], v[32:35]
	v_mfma_f32_16x16x32_bf16 v[20:23], v[132:135], v[210:213], v[20:23]
	v_mfma_f32_16x16x32_bf16 v[16:19], v[140:143], v[210:213], v[16:19]
	v_mfma_f32_16x16x32_bf16 v[4:7], v[132:135], v[218:221], v[4:7]
	v_mfma_f32_16x16x32_bf16 v[0:3], v[140:143], v[218:221], v[0:3]
	s_setprio 0
	s_barrier
	s_add_i32 s6, 0, 0x18000
	s_add_i32 s7, 0, 0x1c000
	v_add_u32_e32 v140, s6, v176
	v_add_u32_e32 v156, s7, v176
	ds_read_b128 v[128:131], v140
	ds_read_b128 v[132:135], v140 offset:1024
	ds_read_b128 v[136:139], v140 offset:2048
	ds_read_b128 v[140:143], v140 offset:3072
	ds_read_b128 v[144:147], v156
	ds_read_b128 v[148:151], v156 offset:1024
	ds_read_b128 v[152:155], v156 offset:2048
	ds_read_b128 v[156:159], v156 offset:3072
	s_mov_b32 m0, s40
	ds_read_b128 v[190:193], v180 offset:32768
	ds_read_b128 v[194:197], v180 offset:33792
	ds_read_b128 v[198:201], v180 offset:34816
	ds_read_b128 v[202:205], v180 offset:35840
	ds_read_b128 v[206:209], v180 offset:36864
	ds_read_b128 v[210:213], v180 offset:37888
	ds_read_b128 v[214:217], v180 offset:38912
	ds_read_b128 v[218:221], v180 offset:39936
	global_load_lds_dwordx4 v168, s[98:99]
	s_mov_b32 m0, s41
	s_nop 0
	global_load_lds_dwordx4 v170, s[98:99]
	s_mov_b32 m0, s34
	s_nop 0
	global_load_lds_dwordx4 v164, s[98:99]
	s_mov_b32 m0, s39
	s_nop 0
	global_load_lds_dwordx4 v166, s[98:99]
	s_waitcnt vmcnt(8)
	s_waitcnt lgkmcnt(0)
	s_barrier
	s_setprio 1
	s_waitcnt lgkmcnt(0)
	v_mfma_f32_16x16x32_bf16 v[124:127], v[128:131], v[190:193], v[124:127]
	v_mfma_f32_16x16x32_bf16 v[120:123], v[136:139], v[190:193], v[120:123]
	v_mfma_f32_16x16x32_bf16 v[108:111], v[128:131], v[198:201], v[108:111]
	v_mfma_f32_16x16x32_bf16 v[104:107], v[136:139], v[198:201], v[104:107]
	v_mfma_f32_16x16x32_bf16 v[92:95], v[128:131], v[206:209], v[92:95]
	v_mfma_f32_16x16x32_bf16 v[88:91], v[136:139], v[206:209], v[88:91]
	v_mfma_f32_16x16x32_bf16 v[76:79], v[128:131], v[214:217], v[76:79]
	v_mfma_f32_16x16x32_bf16 v[72:75], v[136:139], v[214:217], v[72:75]
	v_mfma_f32_16x16x32_bf16 v[124:127], v[132:135], v[194:197], v[124:127]
	v_mfma_f32_16x16x32_bf16 v[120:123], v[140:143], v[194:197], v[120:123]
	v_mfma_f32_16x16x32_bf16 v[108:111], v[132:135], v[202:205], v[108:111]
	v_mfma_f32_16x16x32_bf16 v[104:107], v[140:143], v[202:205], v[104:107]
	v_mfma_f32_16x16x32_bf16 v[92:95], v[132:135], v[210:213], v[92:95]
	v_mfma_f32_16x16x32_bf16 v[88:91], v[140:143], v[210:213], v[88:91]
	v_mfma_f32_16x16x32_bf16 v[76:79], v[132:135], v[218:221], v[76:79]
	v_mfma_f32_16x16x32_bf16 v[72:75], v[140:143], v[218:221], v[72:75]
	v_mfma_f32_16x16x32_bf16 v[116:119], v[144:147], v[190:193], v[116:119]
	v_mfma_f32_16x16x32_bf16 v[112:115], v[152:155], v[190:193], v[112:115]
	v_mfma_f32_16x16x32_bf16 v[100:103], v[144:147], v[198:201], v[100:103]
	v_mfma_f32_16x16x32_bf16 v[96:99], v[152:155], v[198:201], v[96:99]
	v_mfma_f32_16x16x32_bf16 v[84:87], v[144:147], v[206:209], v[84:87]
	v_mfma_f32_16x16x32_bf16 v[80:83], v[152:155], v[206:209], v[80:83]
	v_mfma_f32_16x16x32_bf16 v[68:71], v[144:147], v[214:217], v[68:71]
	v_mfma_f32_16x16x32_bf16 v[64:67], v[152:155], v[214:217], v[64:67]
	v_mfma_f32_16x16x32_bf16 v[116:119], v[148:151], v[194:197], v[116:119]
	v_mfma_f32_16x16x32_bf16 v[112:115], v[156:159], v[194:197], v[112:115]
	v_mfma_f32_16x16x32_bf16 v[100:103], v[148:151], v[202:205], v[100:103]
	v_mfma_f32_16x16x32_bf16 v[96:99], v[156:159], v[202:205], v[96:99]
	v_mfma_f32_16x16x32_bf16 v[84:87], v[148:151], v[210:213], v[84:87]
	v_mfma_f32_16x16x32_bf16 v[80:83], v[156:159], v[210:213], v[80:83]
	v_mfma_f32_16x16x32_bf16 v[68:71], v[148:151], v[218:221], v[68:71]
	v_mfma_f32_16x16x32_bf16 v[64:67], v[156:159], v[218:221], v[64:67]
	s_setprio 0
	s_barrier
	s_add_i32 s6, s6, s84
	s_add_u32 s100, s0, s14
	s_addc_u32 s101, s1, s15
	s_add_u32 s98, s98, s14
	s_addc_u32 s99, s99, s15
	s_mov_b32 m0, s6
	ds_read_b128 v[190:193], v180 offset:49152
	ds_read_b128 v[194:197], v180 offset:50176
	ds_read_b128 v[198:201], v180 offset:51200
	ds_read_b128 v[202:205], v180 offset:52224
	ds_read_b128 v[206:209], v180 offset:53248
	ds_read_b128 v[210:213], v180 offset:54272
	ds_read_b128 v[214:217], v180 offset:55296
	ds_read_b128 v[218:221], v180 offset:56320
	global_load_lds_dwordx4 v160, s[100:101]
	s_add_i32 m0, s6, 0x2000
	s_add_u32 s0, s0, 0x40080
	s_addc_u32 s1, s1, 0
	s_add_i32 s6, s7, s84
	global_load_lds_dwordx4 v162, s[100:101]
	s_mov_b32 m0, s6
	s_nop 0
	global_load_lds_dwordx4 v160, s[0:1]
	s_add_i32 m0, s6, 0x2000
	s_nop 0
	global_load_lds_dwordx4 v162, s[0:1]
	s_mov_b32 m0, s42
	s_nop 0
	global_load_lds_dwordx4 v164, s[98:99]
	s_mov_b32 m0, s43
	s_nop 0
	global_load_lds_dwordx4 v166, s[98:99]
	s_waitcnt vmcnt(6)
	s_waitcnt lgkmcnt(0)
	s_barrier
	s_setprio 1
	s_waitcnt lgkmcnt(0)
	v_mfma_f32_16x16x32_bf16 v[60:63], v[128:131], v[190:193], v[60:63]
	v_mfma_f32_16x16x32_bf16 v[56:59], v[136:139], v[190:193], v[56:59]
	v_mfma_f32_16x16x32_bf16 v[44:47], v[128:131], v[198:201], v[44:47]
	v_mfma_f32_16x16x32_bf16 v[40:43], v[136:139], v[198:201], v[40:43]
	v_mfma_f32_16x16x32_bf16 v[28:31], v[128:131], v[206:209], v[28:31]
	v_mfma_f32_16x16x32_bf16 v[24:27], v[136:139], v[206:209], v[24:27]
	v_mfma_f32_16x16x32_bf16 v[12:15], v[128:131], v[214:217], v[12:15]
	v_mfma_f32_16x16x32_bf16 v[8:11], v[136:139], v[214:217], v[8:11]
	v_mfma_f32_16x16x32_bf16 v[60:63], v[132:135], v[194:197], v[60:63]
	v_mfma_f32_16x16x32_bf16 v[56:59], v[140:143], v[194:197], v[56:59]
	v_mfma_f32_16x16x32_bf16 v[44:47], v[132:135], v[202:205], v[44:47]
	v_mfma_f32_16x16x32_bf16 v[40:43], v[140:143], v[202:205], v[40:43]
	v_mfma_f32_16x16x32_bf16 v[28:31], v[132:135], v[210:213], v[28:31]
	v_mfma_f32_16x16x32_bf16 v[24:27], v[140:143], v[210:213], v[24:27]
	v_mfma_f32_16x16x32_bf16 v[12:15], v[132:135], v[218:221], v[12:15]
	v_mfma_f32_16x16x32_bf16 v[8:11], v[140:143], v[218:221], v[8:11]
	v_mfma_f32_16x16x32_bf16 v[52:55], v[144:147], v[190:193], v[52:55]
	v_mfma_f32_16x16x32_bf16 v[48:51], v[152:155], v[190:193], v[48:51]
	v_mfma_f32_16x16x32_bf16 v[36:39], v[144:147], v[198:201], v[36:39]
	v_mfma_f32_16x16x32_bf16 v[32:35], v[152:155], v[198:201], v[32:35]
	v_mfma_f32_16x16x32_bf16 v[20:23], v[144:147], v[206:209], v[20:23]
	v_mfma_f32_16x16x32_bf16 v[16:19], v[152:155], v[206:209], v[16:19]
	v_mfma_f32_16x16x32_bf16 v[4:7], v[144:147], v[214:217], v[4:7]
	v_mfma_f32_16x16x32_bf16 v[0:3], v[152:155], v[214:217], v[0:3]
	v_mfma_f32_16x16x32_bf16 v[52:55], v[148:151], v[194:197], v[52:55]
	v_mfma_f32_16x16x32_bf16 v[48:51], v[156:159], v[194:197], v[48:51]
	v_mfma_f32_16x16x32_bf16 v[36:39], v[148:151], v[202:205], v[36:39]
	v_mfma_f32_16x16x32_bf16 v[32:35], v[156:159], v[202:205], v[32:35]
	v_mfma_f32_16x16x32_bf16 v[20:23], v[148:151], v[210:213], v[20:23]
	v_mfma_f32_16x16x32_bf16 v[16:19], v[156:159], v[210:213], v[16:19]
	v_mfma_f32_16x16x32_bf16 v[4:7], v[148:151], v[218:221], v[4:7]
	v_mfma_f32_16x16x32_bf16 v[0:3], v[156:159], v[218:221], v[0:3]
	s_setprio 0
	s_barrier
	s_add_i32 s54, s54, 2
	s_cmp_gt_u32 s54, 13
	s_cbranch_scc1 .LBB0_66
	s_mov_b64 s[0:1], s[4:5]
	s_branch .LBB0_61

.LBB0_715:
	s_mov_b64 s[6:7], 0x80
	s_add_i32 m0, s27, 0x18000
	v_lshl_add_u64 v[6:7], v[6:7], 0, s[6:7]
	s_waitcnt vmcnt(2)
	s_barrier
	global_load_lds_dwordx4 v[6:7], off
	v_lshl_add_u64 v[4:5], v[4:5], 0, s[6:7]
	s_add_i32 m0, s27, 0x1a000
	s_add_i32 s37, s27, 0x8000
	s_add_i32 s38, s27, 0xa000
	global_load_lds_dwordx4 v[4:5], off
	v_lshl_add_u64 v[0:1], v[0:1], 0, s[6:7]
	s_mov_b32 m0, s37
	s_add_u32 s8, s20, 0x40080
	global_load_lds_dwordx4 v[0:1], off
	v_lshl_add_u64 v[0:1], v[2:3], 0, s[6:7]
	s_mov_b32 m0, s38
	s_addc_u32 s9, s21, 0
	global_load_lds_dwordx4 v[0:1], off
	s_add_i32 m0, s27, 0x1c000
	v_lshl_add_u64 v[0:1], s[8:9], 0, v[162:163]
	global_load_lds_dwordx4 v[0:1], off
	v_lshl_add_u64 v[0:1], s[8:9], 0, v[160:161]
	s_add_i32 m0, s27, 0x1e000
	s_sext_i32_i8 s45, s0
	global_load_lds_dwordx4 v[0:1], off
	v_and_b32_e32 v0, 15, v8
	v_or_b32_e32 v1, s91, v0
	v_and_b32_e32 v2, 48, v8
	v_lshlrev_b32_e32 v3, 6, v1
	s_movk_i32 s0, 0x3c0
	v_and_or_b32 v3, v3, s0, v2
	v_lshl_or_b32 v0, v0, 6, v2
	v_lshlrev_b32_e32 v2, 2, v8
	s_cmpk_lt_u32 s76, 0x100
	v_lshlrev_b32_e32 v1, 2, v1
	v_and_b32_e32 v2, 32, v2
	s_cselect_b64 s[8:9], -1, 0
	s_add_u32 s10, s66, 0xf800000
	v_and_b32_e32 v1, 32, v1
	v_readlane_b32 s0, v253, 38
	v_bitop3_b32 v176, v0, s74, v2 bitop3:0xde
	s_waitcnt vmcnt(6)
	s_addc_u32 s11, s67, 0
	v_bitop3_b32 v1, v3, s0, v1 bitop3:0xde
	s_add_u32 s40, s66, 0x19400080
	v_add_u32_e32 v0, 0, v176
	s_mov_b32 s39, 0x8000
	s_addc_u32 s41, s67, 0
	v_add_u32_e32 v177, 0x10000, v0
	v_add_u32_e32 v178, 0x14000, v0
	v_add_u32_e32 v179, 0, v1
	s_mov_b32 s12, 0x3f9837f0
	s_mov_b32 s42, 0
	s_barrier
	v_add_u32_e32 v247, s33, v174
	v_bfe_u32 v248, v247, 6, 1
	v_and_b32_e32 v249, 3, v247
	v_bfe_u32 v250, v247, 5, 1
	v_lshlrev_b32_e32 v249, 4, v249
	v_lshlrev_b32_e32 v250, 5, v250
	v_xor_b32_e32 v249, v249, v250
	v_lshl_add_u32 v248, v248, 6, v249
	v_lshrrev_b32_e32 v249, 7, v247
	v_bfe_u32 v247, v247, 2, 4
	v_lshl_add_u32 v247, v249, 4, v247
	v_lshl_add_u32 v247, v247, 11, v248
	s_waitcnt vmcnt(0)
	s_branch .LBB0_718

.LBB0_720:
	s_ashr_i32 s15, s14, 31
	s_lshl_b64 s[18:19], s[14:15], 19
	s_add_u32 s18, s13, s18
	s_addc_u32 s19, s26, s19
	s_and_b64 s[22:23], s[16:17], exec
	s_cselect_b32 s15, s19, s21
	s_cselect_b32 s46, s18, s20
	s_lshl_b32 s47, s43, 8
	s_or_b32 s48, s47, 0x80
	s_add_u32 s49, s20, 0x100
	s_addc_u32 s50, s21, 0
	s_mov_b32 s51, -2
	s_mov_b64 s[20:21], 0
	s_waitcnt vmcnt(0)
	ds_read_b128 v[144:147], v177
	ds_read_b128 v[148:151], v177 offset:1024
	ds_read_b128 v[152:155], v177 offset:2048
	ds_read_b128 v[156:159], v177 offset:3072
	ds_read_b128 v[128:131], v178
	ds_read_b128 v[132:135], v178 offset:1024
	ds_read_b128 v[136:139], v178 offset:2048
	ds_read_b128 v[140:143], v178 offset:3072
	s_cmp_eq_u32 s51, 12
	s_cselect_b64 s[24:25], -1, 0
	s_add_i32 m0, s27, 0xc000
	s_add_u32 s22, s40, s20
	s_addc_u32 s23, s41, s21
	ds_read_b128 v[180:183], v179
	ds_read_b128 v[184:187], v179 offset:1024
	ds_read_b128 v[188:191], v179 offset:2048
	ds_read_b128 v[192:195], v179 offset:3072
	ds_read_b128 v[196:199], v179 offset:4096
	ds_read_b128 v[200:203], v179 offset:5120
	ds_read_b128 v[204:207], v179 offset:6144
	ds_read_b128 v[208:211], v179 offset:7168
	global_load_lds_dwordx4 v168, s[22:23]
	s_add_i32 m0, s27, 0xe000
	s_nop 0
	global_load_lds_dwordx4 v170, s[22:23]
	s_waitcnt vmcnt(40)
	s_waitcnt lgkmcnt(0)
	s_barrier
	s_setprio 1
	s_waitcnt lgkmcnt(0)
	v_mfma_f32_16x16x32_bf16 v[124:127], v[144:147], v[180:183], 0
	v_mfma_f32_16x16x32_bf16 v[120:123], v[152:155], v[180:183], 0
	v_mfma_f32_16x16x32_bf16 v[112:115], v[144:147], v[188:191], 0
	v_mfma_f32_16x16x32_bf16 v[104:107], v[152:155], v[188:191], 0
	v_mfma_f32_16x16x32_bf16 v[96:99], v[144:147], v[196:199], 0
	v_mfma_f32_16x16x32_bf16 v[88:91], v[152:155], v[196:199], 0
	v_mfma_f32_16x16x32_bf16 v[80:83], v[144:147], v[204:207], 0
	v_mfma_f32_16x16x32_bf16 v[72:75], v[152:155], v[204:207], 0
	v_mfma_f32_16x16x32_bf16 v[124:127], v[148:151], v[184:187], v[124:127]
	v_mfma_f32_16x16x32_bf16 v[120:123], v[156:159], v[184:187], v[120:123]
	v_mfma_f32_16x16x32_bf16 v[112:115], v[148:151], v[192:195], v[112:115]
	v_mfma_f32_16x16x32_bf16 v[104:107], v[156:159], v[192:195], v[104:107]
	v_mfma_f32_16x16x32_bf16 v[96:99], v[148:151], v[200:203], v[96:99]
	v_mfma_f32_16x16x32_bf16 v[88:91], v[156:159], v[200:203], v[88:91]
	v_mfma_f32_16x16x32_bf16 v[80:83], v[148:151], v[208:211], v[80:83]
	v_mfma_f32_16x16x32_bf16 v[72:75], v[156:159], v[208:211], v[72:75]
	v_mfma_f32_16x16x32_bf16 v[116:119], v[128:131], v[180:183], 0
	v_mfma_f32_16x16x32_bf16 v[108:111], v[136:139], v[180:183], 0
	v_mfma_f32_16x16x32_bf16 v[100:103], v[128:131], v[188:191], 0
	v_mfma_f32_16x16x32_bf16 v[92:95], v[136:139], v[188:191], 0
	v_mfma_f32_16x16x32_bf16 v[84:87], v[128:131], v[196:199], 0
	v_mfma_f32_16x16x32_bf16 v[76:79], v[136:139], v[196:199], 0
	v_mfma_f32_16x16x32_bf16 v[68:71], v[128:131], v[204:207], 0
	v_mfma_f32_16x16x32_bf16 v[64:67], v[136:139], v[204:207], 0
	v_mfma_f32_16x16x32_bf16 v[116:119], v[132:135], v[184:187], v[116:119]
	v_mfma_f32_16x16x32_bf16 v[108:111], v[140:143], v[184:187], v[108:111]
	v_mfma_f32_16x16x32_bf16 v[100:103], v[132:135], v[192:195], v[100:103]
	v_mfma_f32_16x16x32_bf16 v[92:95], v[140:143], v[192:195], v[92:95]
	v_mfma_f32_16x16x32_bf16 v[84:87], v[132:135], v[200:203], v[84:87]
	v_mfma_f32_16x16x32_bf16 v[76:79], v[140:143], v[200:203], v[76:79]
	v_mfma_f32_16x16x32_bf16 v[68:71], v[132:135], v[208:211], v[68:71]
	v_mfma_f32_16x16x32_bf16 v[64:67], v[140:143], v[208:211], v[64:67]
	s_setprio 0
	s_barrier
	s_and_b64 s[22:23], s[16:17], s[24:25]
	s_andn2_b64 vcc, exec, s[22:23]
	s_cbranch_vccnz .Lpk1_LBB0_723
	s_lshl_b32 s57, s47, 11
	s_lshl_b32 s58, s48, 11
	v_add_u32_e32 v164, s57, v247
	v_add_u32_e32 v168, s58, v247
	v_add_u32_e32 v166, 0x20000, v164
	v_add_u32_e32 v170, 0x20000, v168
	s_branch .Lpk1_LBB0_724
.Lpk1_LBB0_723:
.Lpk1_LBB0_724:
	s_add_u32 s22, s20, 0x100
	s_addc_u32 s23, s21, 0
	s_and_b64 s[52:53], s[24:25], exec
	s_cselect_b32 s0, 0, s22
	s_add_u32 s52, s49, s20
	s_addc_u32 s53, s50, s21
	s_and_b64 s[20:21], s[24:25], exec
	s_cselect_b32 s21, s15, s53
	s_cselect_b32 s20, s46, s52
	s_add_u32 s98, s2, s0
	s_addc_u32 s99, s3, s1
	s_mov_b32 m0, s28
	s_add_u32 s24, s20, 0x40000
	ds_read_b128 v[180:183], v179 offset:16384
	ds_read_b128 v[184:187], v179 offset:17408
	ds_read_b128 v[188:191], v179 offset:18432
	ds_read_b128 v[192:195], v179 offset:19456
	ds_read_b128 v[196:199], v179 offset:20480
	ds_read_b128 v[200:203], v179 offset:21504
	ds_read_b128 v[204:207], v179 offset:22528
	ds_read_b128 v[208:211], v179 offset:23552
	global_load_lds_dwordx4 v162, s[20:21]
	s_mov_b32 m0, s29
	s_addc_u32 s25, s21, 0
	global_load_lds_dwordx4 v160, s[20:21]
	s_mov_b32 m0, s30
	s_nop 0
	global_load_lds_dwordx4 v162, s[24:25]
	s_mov_b32 m0, s31
	s_nop 0
	global_load_lds_dwordx4 v160, s[24:25]
	s_waitcnt vmcnt(38)
	s_waitcnt lgkmcnt(0)
	s_barrier
	s_setprio 1
	s_waitcnt lgkmcnt(0)
	v_mfma_f32_16x16x32_bf16 v[60:63], v[144:147], v[180:183], 0
	v_mfma_f32_16x16x32_bf16 v[56:59], v[152:155], v[180:183], 0
	v_mfma_f32_16x16x32_bf16 v[48:51], v[144:147], v[188:191], 0
	v_mfma_f32_16x16x32_bf16 v[40:43], v[152:155], v[188:191], 0
	v_mfma_f32_16x16x32_bf16 v[32:35], v[144:147], v[196:199], 0
	v_mfma_f32_16x16x32_bf16 v[24:27], v[152:155], v[196:199], 0
	v_mfma_f32_16x16x32_bf16 v[16:19], v[144:147], v[204:207], 0
	v_mfma_f32_16x16x32_bf16 v[8:11], v[152:155], v[204:207], 0
	v_mfma_f32_16x16x32_bf16 v[60:63], v[148:151], v[184:187], v[60:63]
	v_mfma_f32_16x16x32_bf16 v[56:59], v[156:159], v[184:187], v[56:59]
	v_mfma_f32_16x16x32_bf16 v[48:51], v[148:151], v[192:195], v[48:51]
	v_mfma_f32_16x16x32_bf16 v[40:43], v[156:159], v[192:195], v[40:43]
	v_mfma_f32_16x16x32_bf16 v[32:35], v[148:151], v[200:203], v[32:35]
	v_mfma_f32_16x16x32_bf16 v[24:27], v[156:159], v[200:203], v[24:27]
	v_mfma_f32_16x16x32_bf16 v[16:19], v[148:151], v[208:211], v[16:19]
	v_mfma_f32_16x16x32_bf16 v[8:11], v[156:159], v[208:211], v[8:11]
	v_mfma_f32_16x16x32_bf16 v[52:55], v[128:131], v[180:183], 0
	v_mfma_f32_16x16x32_bf16 v[44:47], v[136:139], v[180:183], 0
	v_mfma_f32_16x16x32_bf16 v[36:39], v[128:131], v[188:191], 0
	v_mfma_f32_16x16x32_bf16 v[28:31], v[136:139], v[188:191], 0
	v_mfma_f32_16x16x32_bf16 v[20:23], v[128:131], v[196:199], 0
	v_mfma_f32_16x16x32_bf16 v[12:15], v[136:139], v[196:199], 0
	v_mfma_f32_16x16x32_bf16 v[4:7], v[128:131], v[204:207], 0
	v_mfma_f32_16x16x32_bf16 v[0:3], v[136:139], v[204:207], 0
	v_mfma_f32_16x16x32_bf16 v[52:55], v[132:135], v[184:187], v[52:55]
	v_mfma_f32_16x16x32_bf16 v[44:47], v[140:143], v[184:187], v[44:47]
	v_mfma_f32_16x16x32_bf16 v[36:39], v[132:135], v[192:195], v[36:39]
	v_mfma_f32_16x16x32_bf16 v[28:31], v[140:143], v[192:195], v[28:31]
	v_mfma_f32_16x16x32_bf16 v[20:23], v[132:135], v[200:203], v[20:23]
	v_mfma_f32_16x16x32_bf16 v[12:15], v[140:143], v[200:203], v[12:15]
	v_mfma_f32_16x16x32_bf16 v[4:7], v[132:135], v[208:211], v[4:7]
	v_mfma_f32_16x16x32_bf16 v[0:3], v[140:143], v[208:211], v[0:3]
	s_setprio 0
	s_barrier
	s_add_i32 s24, 0, 0x18000
	s_add_i32 s25, 0, 0x1c000
	v_add_u32_e32 v140, s24, v176
	v_add_u32_e32 v156, s25, v176
	ds_read_b128 v[128:131], v140
	ds_read_b128 v[132:135], v140 offset:1024
	ds_read_b128 v[136:139], v140 offset:2048
	ds_read_b128 v[140:143], v140 offset:3072
	ds_read_b128 v[144:147], v156
	ds_read_b128 v[148:151], v156 offset:1024
	ds_read_b128 v[152:155], v156 offset:2048
	ds_read_b128 v[156:159], v156 offset:3072
	s_mov_b32 m0, s35
	ds_read_b128 v[180:183], v179 offset:32768
	ds_read_b128 v[184:187], v179 offset:33792
	ds_read_b128 v[188:191], v179 offset:34816
	ds_read_b128 v[192:195], v179 offset:35840
	ds_read_b128 v[196:199], v179 offset:36864
	ds_read_b128 v[200:203], v179 offset:37888
	ds_read_b128 v[204:207], v179 offset:38912
	ds_read_b128 v[208:211], v179 offset:39936
	global_load_lds_dwordx4 v168, s[98:99]
	s_mov_b32 m0, s36
	s_nop 0
	global_load_lds_dwordx4 v170, s[98:99]
	s_mov_b32 m0, s27
	s_nop 0
	global_load_lds_dwordx4 v164, s[98:99]
	s_mov_b32 m0, s34
	s_nop 0
	global_load_lds_dwordx4 v166, s[98:99]
	s_waitcnt vmcnt(8)
	s_waitcnt lgkmcnt(0)
	s_barrier
	s_setprio 1
	s_waitcnt lgkmcnt(0)
	v_mfma_f32_16x16x32_bf16 v[124:127], v[128:131], v[180:183], v[124:127]
	v_mfma_f32_16x16x32_bf16 v[120:123], v[136:139], v[180:183], v[120:123]
	v_mfma_f32_16x16x32_bf16 v[112:115], v[128:131], v[188:191], v[112:115]
	v_mfma_f32_16x16x32_bf16 v[104:107], v[136:139], v[188:191], v[104:107]
	v_mfma_f32_16x16x32_bf16 v[96:99], v[128:131], v[196:199], v[96:99]
	v_mfma_f32_16x16x32_bf16 v[88:91], v[136:139], v[196:199], v[88:91]
	v_mfma_f32_16x16x32_bf16 v[80:83], v[128:131], v[204:207], v[80:83]
	v_mfma_f32_16x16x32_bf16 v[72:75], v[136:139], v[204:207], v[72:75]
	v_mfma_f32_16x16x32_bf16 v[124:127], v[132:135], v[184:187], v[124:127]
	v_mfma_f32_16x16x32_bf16 v[120:123], v[140:143], v[184:187], v[120:123]
	v_mfma_f32_16x16x32_bf16 v[112:115], v[132:135], v[192:195], v[112:115]
	v_mfma_f32_16x16x32_bf16 v[104:107], v[140:143], v[192:195], v[104:107]
	v_mfma_f32_16x16x32_bf16 v[96:99], v[132:135], v[200:203], v[96:99]
	v_mfma_f32_16x16x32_bf16 v[88:91], v[140:143], v[200:203], v[88:91]
	v_mfma_f32_16x16x32_bf16 v[80:83], v[132:135], v[208:211], v[80:83]
	v_mfma_f32_16x16x32_bf16 v[72:75], v[140:143], v[208:211], v[72:75]
	v_mfma_f32_16x16x32_bf16 v[116:119], v[144:147], v[180:183], v[116:119]
	v_mfma_f32_16x16x32_bf16 v[108:111], v[152:155], v[180:183], v[108:111]
	v_mfma_f32_16x16x32_bf16 v[100:103], v[144:147], v[188:191], v[100:103]
	v_mfma_f32_16x16x32_bf16 v[92:95], v[152:155], v[188:191], v[92:95]
	v_mfma_f32_16x16x32_bf16 v[84:87], v[144:147], v[196:199], v[84:87]
	v_mfma_f32_16x16x32_bf16 v[76:79], v[152:155], v[196:199], v[76:79]
	v_mfma_f32_16x16x32_bf16 v[68:71], v[144:147], v[204:207], v[68:71]
	v_mfma_f32_16x16x32_bf16 v[64:67], v[152:155], v[204:207], v[64:67]
	v_mfma_f32_16x16x32_bf16 v[116:119], v[148:151], v[184:187], v[116:119]
	v_mfma_f32_16x16x32_bf16 v[108:111], v[156:159], v[184:187], v[108:111]
	v_mfma_f32_16x16x32_bf16 v[100:103], v[148:151], v[192:195], v[100:103]
	v_mfma_f32_16x16x32_bf16 v[92:95], v[156:159], v[192:195], v[92:95]
	v_mfma_f32_16x16x32_bf16 v[84:87], v[148:151], v[200:203], v[84:87]
	v_mfma_f32_16x16x32_bf16 v[76:79], v[156:159], v[200:203], v[76:79]
	v_mfma_f32_16x16x32_bf16 v[68:71], v[148:151], v[208:211], v[68:71]
	v_mfma_f32_16x16x32_bf16 v[64:67], v[156:159], v[208:211], v[64:67]
	s_setprio 0
	s_barrier
	s_add_i32 s0, s24, s84
	s_add_u32 s100, s20, s6
	s_addc_u32 s101, s21, s7
	s_add_u32 s98, s98, s6
	s_addc_u32 s99, s99, s7
	s_mov_b32 m0, s0
	ds_read_b128 v[180:183], v179 offset:49152
	ds_read_b128 v[184:187], v179 offset:50176
	ds_read_b128 v[188:191], v179 offset:51200
	ds_read_b128 v[192:195], v179 offset:52224
	ds_read_b128 v[196:199], v179 offset:53248
	ds_read_b128 v[200:203], v179 offset:54272
	ds_read_b128 v[204:207], v179 offset:55296
	ds_read_b128 v[208:211], v179 offset:56320
	global_load_lds_dwordx4 v162, s[100:101]
	s_add_i32 m0, s0, 0x2000
	s_add_u32 s20, s20, 0x40080
	s_addc_u32 s21, s21, 0
	s_add_i32 s0, s25, s84
	global_load_lds_dwordx4 v160, s[100:101]
	s_mov_b32 m0, s0
	s_nop 0
	global_load_lds_dwordx4 v162, s[20:21]
	s_add_i32 m0, s0, 0x2000
	s_nop 0
	global_load_lds_dwordx4 v160, s[20:21]
	s_mov_b32 m0, s37
	s_nop 0
	global_load_lds_dwordx4 v164, s[98:99]
	s_mov_b32 m0, s38
	s_nop 0
	global_load_lds_dwordx4 v166, s[98:99]
	s_waitcnt vmcnt(6)
	s_waitcnt lgkmcnt(0)
	s_barrier
	s_setprio 1
	s_waitcnt lgkmcnt(0)
	v_mfma_f32_16x16x32_bf16 v[60:63], v[128:131], v[180:183], v[60:63]
	v_mfma_f32_16x16x32_bf16 v[56:59], v[136:139], v[180:183], v[56:59]
	v_mfma_f32_16x16x32_bf16 v[48:51], v[128:131], v[188:191], v[48:51]
	v_mfma_f32_16x16x32_bf16 v[40:43], v[136:139], v[188:191], v[40:43]
	v_mfma_f32_16x16x32_bf16 v[32:35], v[128:131], v[196:199], v[32:35]
	v_mfma_f32_16x16x32_bf16 v[24:27], v[136:139], v[196:199], v[24:27]
	v_mfma_f32_16x16x32_bf16 v[16:19], v[128:131], v[204:207], v[16:19]
	v_mfma_f32_16x16x32_bf16 v[8:11], v[136:139], v[204:207], v[8:11]
	v_mfma_f32_16x16x32_bf16 v[60:63], v[132:135], v[184:187], v[60:63]
	v_mfma_f32_16x16x32_bf16 v[56:59], v[140:143], v[184:187], v[56:59]
	v_mfma_f32_16x16x32_bf16 v[48:51], v[132:135], v[192:195], v[48:51]
	v_mfma_f32_16x16x32_bf16 v[40:43], v[140:143], v[192:195], v[40:43]
	v_mfma_f32_16x16x32_bf16 v[32:35], v[132:135], v[200:203], v[32:35]
	v_mfma_f32_16x16x32_bf16 v[24:27], v[140:143], v[200:203], v[24:27]
	v_mfma_f32_16x16x32_bf16 v[16:19], v[132:135], v[208:211], v[16:19]
	v_mfma_f32_16x16x32_bf16 v[8:11], v[140:143], v[208:211], v[8:11]
	v_mfma_f32_16x16x32_bf16 v[52:55], v[144:147], v[180:183], v[52:55]
	v_mfma_f32_16x16x32_bf16 v[44:47], v[152:155], v[180:183], v[44:47]
	v_mfma_f32_16x16x32_bf16 v[36:39], v[144:147], v[188:191], v[36:39]
	v_mfma_f32_16x16x32_bf16 v[28:31], v[152:155], v[188:191], v[28:31]
	v_mfma_f32_16x16x32_bf16 v[20:23], v[144:147], v[196:199], v[20:23]
	v_mfma_f32_16x16x32_bf16 v[12:15], v[152:155], v[196:199], v[12:15]
	v_mfma_f32_16x16x32_bf16 v[4:7], v[144:147], v[204:207], v[4:7]
	v_mfma_f32_16x16x32_bf16 v[0:3], v[152:155], v[204:207], v[0:3]
	v_mfma_f32_16x16x32_bf16 v[52:55], v[148:151], v[184:187], v[52:55]
	v_mfma_f32_16x16x32_bf16 v[44:47], v[156:159], v[184:187], v[44:47]
	v_mfma_f32_16x16x32_bf16 v[36:39], v[148:151], v[192:195], v[36:39]
	v_mfma_f32_16x16x32_bf16 v[28:31], v[156:159], v[192:195], v[28:31]
	v_mfma_f32_16x16x32_bf16 v[20:23], v[148:151], v[200:203], v[20:23]
	v_mfma_f32_16x16x32_bf16 v[12:15], v[156:159], v[200:203], v[12:15]
	v_mfma_f32_16x16x32_bf16 v[4:7], v[148:151], v[208:211], v[4:7]
	v_mfma_f32_16x16x32_bf16 v[0:3], v[156:159], v[208:211], v[0:3]
	s_setprio 0
	s_barrier
	s_add_i32 s51, s51, 2
	s_cmp_gt_u32 s51, 13
	s_cbranch_scc1 .LBB0_726
	s_mov_b64 s[20:21], s[22:23]
	s_branch .LBB0_721

.LBB0_1242:
	s_mov_b64 s[10:11], 0x80
	s_add_i32 m0, s28, 0x18000
	v_lshl_add_u64 v[6:7], v[6:7], 0, s[10:11]
	s_waitcnt vmcnt(2)
	s_barrier
	global_load_lds_dwordx4 v[6:7], off
	v_lshl_add_u64 v[2:3], v[2:3], 0, s[10:11]
	s_add_i32 m0, s28, 0x1a000
	s_add_i32 s38, s28, 0x8000
	s_add_i32 s39, s28, 0xa000
	global_load_lds_dwordx4 v[2:3], off
	v_lshl_add_u64 v[0:1], v[0:1], 0, s[10:11]
	s_mov_b32 m0, s38
	s_add_u32 s12, s22, 0x20080
	global_load_lds_dwordx4 v[0:1], off
	v_lshl_add_u64 v[0:1], v[4:5], 0, s[10:11]
	s_mov_b32 m0, s39
	s_addc_u32 s13, s23, 0
	global_load_lds_dwordx4 v[0:1], off
	s_add_i32 m0, s28, 0x1c000
	v_lshl_add_u64 v[0:1], s[12:13], 0, v[162:163]
	global_load_lds_dwordx4 v[0:1], off
	v_lshl_add_u64 v[0:1], s[12:13], 0, v[160:161]
	s_add_i32 m0, s28, 0x1e000
	v_and_b32_e32 v2, 48, v8
	global_load_lds_dwordx4 v[0:1], off
	v_and_b32_e32 v0, 15, v8
	v_or_b32_e32 v1, s91, v0
	v_lshlrev_b32_e32 v3, 6, v1
	s_movk_i32 s6, 0x3c0
	v_and_or_b32 v3, v3, s6, v2
	v_lshl_or_b32 v0, v0, 6, v2
	v_lshlrev_b32_e32 v2, 2, v8
	v_lshlrev_b32_e32 v1, 2, v1
	v_and_b32_e32 v2, 32, v2
	v_and_b32_e32 v1, 32, v1
	v_readlane_b32 s6, v253, 38
	v_bitop3_b32 v176, v0, s74, v2 bitop3:0xde
	s_waitcnt vmcnt(6)
	s_cmpk_lt_u32 s76, 0x100
	v_bitop3_b32 v1, v3, s6, v1 bitop3:0xde
	s_cselect_b64 s[12:13], -1, 0
	s_add_u32 s40, s66, 0x16000080
	v_add_u32_e32 v0, 0, v176
	s_mov_b32 s69, s7
	s_addc_u32 s41, s67, 0
	v_add_u32_e32 v177, 0x10000, v0
	v_add_u32_e32 v178, 0x14000, v0
	v_add_u32_e32 v179, 0, v1
	s_mov_b32 s14, 0x3d000000
	s_movk_i32 s42, 0xb00
	s_add_i32 s43, s28, 0xc000
	s_add_i32 s44, s28, 0xe000
	s_mov_b32 s45, 0
	s_barrier
	v_add_u32_e32 v247, s33, v174
	v_bfe_u32 v252, v247, 6, 1
	v_and_b32_e32 v248, 3, v247
	v_bfe_u32 v249, v247, 5, 1
	v_lshlrev_b32_e32 v248, 4, v248
	v_lshlrev_b32_e32 v249, 5, v249
	v_xor_b32_e32 v248, v248, v249
	v_lshl_add_u32 v252, v252, 6, v248
	v_lshrrev_b32_e32 v248, 7, v247
	v_bfe_u32 v247, v247, 2, 4
	v_lshl_add_u32 v247, v248, 4, v247
	s_waitcnt vmcnt(0)
	s_branch .LBB0_1245

.Lgu_noidx:
	ds_read_b128 v[16:19], v177
	ds_read_b128 v[20:23], v177 offset:1024
	ds_read_b128 v[24:27], v177 offset:2048
	ds_read_b128 v[28:31], v177 offset:3072
	ds_read_b128 v[0:3], v178
	ds_read_b128 v[4:7], v178 offset:1024
	ds_read_b128 v[8:11], v178 offset:2048
	ds_read_b128 v[12:15], v178 offset:3072
	s_cmp_eq_u32 s57, 4
	s_cselect_b64 s[26:27], -1, 0
	s_add_u32 s24, s40, s22
	s_addc_u32 s25, s41, s23
	s_mov_b32 m0, s43
	ds_read_b128 v[180:183], v179
	ds_read_b128 v[184:187], v179 offset:1024
	ds_read_b128 v[188:191], v179 offset:2048
	ds_read_b128 v[192:195], v179 offset:3072
	ds_read_b128 v[196:199], v179 offset:4096
	ds_read_b128 v[200:203], v179 offset:5120
	ds_read_b128 v[204:207], v179 offset:6144
	ds_read_b128 v[208:211], v179 offset:7168
	global_load_lds_dwordx4 v168, s[24:25]
	s_mov_b32 m0, s44
	s_nop 0
	global_load_lds_dwordx4 v166, s[24:25]
	s_waitcnt vmcnt(16)
	s_waitcnt lgkmcnt(0)
	s_barrier
	s_setprio 1
	s_waitcnt lgkmcnt(0)
	v_mfma_f32_16x16x128_f8f6f4 v[156:159], v[16:23], v[180:187], 0
	v_mfma_f32_16x16x128_f8f6f4 v[152:155], v[24:31], v[180:187], 0
	v_mfma_f32_16x16x128_f8f6f4 v[140:143], v[16:23], v[188:195], 0
	v_mfma_f32_16x16x128_f8f6f4 v[136:139], v[24:31], v[188:195], 0
	v_mfma_f32_16x16x128_f8f6f4 v[124:127], v[16:23], v[196:203], 0
	v_mfma_f32_16x16x128_f8f6f4 v[120:123], v[24:31], v[196:203], 0
	v_mfma_f32_16x16x128_f8f6f4 v[108:111], v[16:23], v[204:211], 0
	v_mfma_f32_16x16x128_f8f6f4 v[104:107], v[24:31], v[204:211], 0
	v_mfma_f32_16x16x128_f8f6f4 v[148:151], v[0:7], v[180:187], 0
	v_mfma_f32_16x16x128_f8f6f4 v[144:147], v[8:15], v[180:187], 0
	v_mfma_f32_16x16x128_f8f6f4 v[132:135], v[0:7], v[188:195], 0
	v_mfma_f32_16x16x128_f8f6f4 v[128:131], v[8:15], v[188:195], 0
	v_mfma_f32_16x16x128_f8f6f4 v[116:119], v[0:7], v[196:203], 0
	v_mfma_f32_16x16x128_f8f6f4 v[112:115], v[8:15], v[196:203], 0
	v_mfma_f32_16x16x128_f8f6f4 v[100:103], v[0:7], v[204:211], 0
	v_mfma_f32_16x16x128_f8f6f4 v[96:99], v[8:15], v[204:211], 0
	s_setprio 0
	s_barrier
	s_and_b64 s[24:25], s[18:19], s[26:27]
	s_andn2_b64 vcc, exec, s[24:25]
	s_cbranch_vccnz .Lpk2_LBB0_1250
	v_lshl_add_u32 v164, v248, 10, v252
	v_lshl_add_u32 v170, v249, 10, v252
	v_lshl_add_u32 v168, v250, 10, v252
	v_lshl_add_u32 v166, v251, 10, v252
	s_branch .Lpk2_LBB0_1251
.Lpk2_LBB0_1250:
.Lpk2_LBB0_1251:
	s_add_u32 s24, s22, 0x100
	s_addc_u32 s25, s23, 0
	s_and_b64 s[70:71], s[26:27], exec
	s_cselect_b32 s6, 0, s24
	s_add_u32 s70, s53, s22
	s_addc_u32 s71, s56, s23
	s_and_b64 s[22:23], s[26:27], exec
	s_cselect_b32 s23, s17, s71
	s_cselect_b32 s22, s50, s70
	s_add_u32 s98, s4, s6
	s_addc_u32 s99, s5, s7
	s_mov_b32 m0, s29
	s_add_u32 s26, s22, 0x20000
	ds_read_b128 v[180:183], v179 offset:16384
	ds_read_b128 v[184:187], v179 offset:17408
	ds_read_b128 v[188:191], v179 offset:18432
	ds_read_b128 v[192:195], v179 offset:19456
	ds_read_b128 v[196:199], v179 offset:20480
	ds_read_b128 v[200:203], v179 offset:21504
	ds_read_b128 v[204:207], v179 offset:22528
	ds_read_b128 v[208:211], v179 offset:23552
	global_load_lds_dwordx4 v162, s[22:23]
	s_mov_b32 m0, s30
	s_addc_u32 s27, s23, 0
	global_load_lds_dwordx4 v160, s[22:23]
	s_mov_b32 m0, s31
	s_nop 0
	global_load_lds_dwordx4 v162, s[26:27]
	s_mov_b32 m0, s34
	s_nop 0
	global_load_lds_dwordx4 v160, s[26:27]
	s_waitcnt vmcnt(14)
	s_waitcnt lgkmcnt(0)
	s_barrier
	s_setprio 1
	s_waitcnt lgkmcnt(0)
	v_mfma_f32_16x16x128_f8f6f4 v[92:95], v[16:23], v[180:187], 0
	v_mfma_f32_16x16x128_f8f6f4 v[88:91], v[24:31], v[180:187], 0
	v_mfma_f32_16x16x128_f8f6f4 v[76:79], v[16:23], v[188:195], 0
	v_mfma_f32_16x16x128_f8f6f4 v[72:75], v[24:31], v[188:195], 0
	v_mfma_f32_16x16x128_f8f6f4 v[212:215], v[16:23], v[196:203], 0
	v_mfma_f32_16x16x128_f8f6f4 v[216:219], v[24:31], v[196:203], 0
	v_mfma_f32_16x16x128_f8f6f4 v[220:223], v[16:23], v[204:211], 0
	v_mfma_f32_16x16x128_f8f6f4 v[224:227], v[24:31], v[204:211], 0
	v_mfma_f32_16x16x128_f8f6f4 v[84:87], v[0:7], v[180:187], 0
	v_mfma_f32_16x16x128_f8f6f4 v[80:83], v[8:15], v[180:187], 0
	v_mfma_f32_16x16x128_f8f6f4 v[68:71], v[0:7], v[188:195], 0
	v_mfma_f32_16x16x128_f8f6f4 v[64:67], v[8:15], v[188:195], 0
	v_mfma_f32_16x16x128_f8f6f4 v[228:231], v[0:7], v[196:203], 0
	v_mfma_f32_16x16x128_f8f6f4 v[196:199], v[8:15], v[196:203], 0
	v_mfma_f32_16x16x128_f8f6f4 v[200:203], v[0:7], v[204:211], 0
	v_mfma_f32_16x16x128_f8f6f4 v[204:207], v[8:15], v[204:211], 0
	s_setprio 0
	s_barrier
	s_add_i32 s26, 0, 0x18000
	s_add_i32 s27, 0, 0x1c000
	v_add_u32_e32 v12, s26, v176
	v_add_u32_e32 v28, s27, v176
	ds_read_b128 v[0:3], v12
	ds_read_b128 v[4:7], v12 offset:1024
	ds_read_b128 v[8:11], v12 offset:2048
	ds_read_b128 v[12:15], v12 offset:3072
	ds_read_b128 v[16:19], v28
	ds_read_b128 v[20:23], v28 offset:1024
	ds_read_b128 v[24:27], v28 offset:2048
	ds_read_b128 v[28:31], v28 offset:3072
	s_mov_b32 m0, s36
	ds_read_b128 v[32:35], v179 offset:32768
	ds_read_b128 v[36:39], v179 offset:33792
	ds_read_b128 v[40:43], v179 offset:34816
	ds_read_b128 v[44:47], v179 offset:35840
	ds_read_b128 v[48:51], v179 offset:36864
	ds_read_b128 v[52:55], v179 offset:37888
	ds_read_b128 v[56:59], v179 offset:38912
	ds_read_b128 v[60:63], v179 offset:39936
	global_load_lds_dwordx4 v168, s[98:99]
	s_mov_b32 m0, s37
	s_nop 0
	global_load_lds_dwordx4 v166, s[98:99]
	s_mov_b32 m0, s28
	s_nop 0
	global_load_lds_dwordx4 v164, s[98:99]
	s_mov_b32 m0, s35
	s_nop 0
	global_load_lds_dwordx4 v170, s[98:99]
	s_waitcnt vmcnt(8)
	s_waitcnt lgkmcnt(0)
	s_barrier
	s_setprio 1
	s_waitcnt lgkmcnt(0)
	v_mfma_f32_16x16x128_f8f6f4 v[156:159], v[0:7], v[32:39], v[156:159]
	v_mfma_f32_16x16x128_f8f6f4 v[152:155], v[8:15], v[32:39], v[152:155]
	v_mfma_f32_16x16x128_f8f6f4 v[140:143], v[0:7], v[40:47], v[140:143]
	v_mfma_f32_16x16x128_f8f6f4 v[136:139], v[8:15], v[40:47], v[136:139]
	v_mfma_f32_16x16x128_f8f6f4 v[124:127], v[0:7], v[48:55], v[124:127]
	v_mfma_f32_16x16x128_f8f6f4 v[120:123], v[8:15], v[48:55], v[120:123]
	v_mfma_f32_16x16x128_f8f6f4 v[108:111], v[0:7], v[56:63], v[108:111]
	v_mfma_f32_16x16x128_f8f6f4 v[104:107], v[8:15], v[56:63], v[104:107]
	v_mfma_f32_16x16x128_f8f6f4 v[148:151], v[16:23], v[32:39], v[148:151]
	v_mfma_f32_16x16x128_f8f6f4 v[144:147], v[24:31], v[32:39], v[144:147]
	v_mfma_f32_16x16x128_f8f6f4 v[132:135], v[16:23], v[40:47], v[132:135]
	v_mfma_f32_16x16x128_f8f6f4 v[128:131], v[24:31], v[40:47], v[128:131]
	v_mfma_f32_16x16x128_f8f6f4 v[116:119], v[16:23], v[48:55], v[116:119]
	v_mfma_f32_16x16x128_f8f6f4 v[112:115], v[24:31], v[48:55], v[112:115]
	v_mfma_f32_16x16x128_f8f6f4 v[100:103], v[16:23], v[56:63], v[100:103]
	v_mfma_f32_16x16x128_f8f6f4 v[96:99], v[24:31], v[56:63], v[96:99]
	s_setprio 0
	s_barrier
	s_add_i32 s6, s26, s84
	s_add_u32 s100, s22, s10
	s_addc_u32 s101, s23, s11
	s_add_u32 s98, s98, s10
	s_addc_u32 s99, s99, s11
	s_mov_b32 m0, s6
	ds_read_b128 v[32:35], v179 offset:49152
	ds_read_b128 v[36:39], v179 offset:50176
	ds_read_b128 v[48:51], v179 offset:51200
	ds_read_b128 v[52:55], v179 offset:52224
	ds_read_b128 v[180:183], v179 offset:53248
	ds_read_b128 v[184:187], v179 offset:54272
	ds_read_b128 v[188:191], v179 offset:55296
	ds_read_b128 v[192:195], v179 offset:56320
	global_load_lds_dwordx4 v162, s[100:101]
	s_add_i32 m0, s6, 0x2000
	s_add_u32 s22, s22, 0x20080
	s_addc_u32 s23, s23, 0
	s_add_i32 s6, s27, s84
	global_load_lds_dwordx4 v160, s[100:101]
	s_mov_b32 m0, s6
	s_nop 0
	global_load_lds_dwordx4 v162, s[22:23]
	s_add_i32 m0, s6, 0x2000
	s_nop 0
	global_load_lds_dwordx4 v160, s[22:23]
	s_mov_b32 m0, s38
	s_nop 0
	global_load_lds_dwordx4 v164, s[98:99]
	s_mov_b32 m0, s39
	s_nop 0
	global_load_lds_dwordx4 v170, s[98:99]
	s_waitcnt vmcnt(6)
	s_waitcnt lgkmcnt(0)
	s_barrier
	s_setprio 1
	s_waitcnt lgkmcnt(0)
	v_mfma_f32_16x16x128_f8f6f4 v[92:95], v[0:7], v[32:39], v[92:95]
	v_mfma_f32_16x16x128_f8f6f4 v[88:91], v[8:15], v[32:39], v[88:91]
	v_mfma_f32_16x16x128_f8f6f4 v[76:79], v[0:7], v[48:55], v[76:79]
	v_mfma_f32_16x16x128_f8f6f4 v[72:75], v[8:15], v[48:55], v[72:75]
	v_mfma_f32_16x16x128_f8f6f4 v[60:63], v[0:7], v[180:187], v[212:215]
	v_mfma_f32_16x16x128_f8f6f4 v[56:59], v[8:15], v[180:187], v[216:219]
	v_mfma_f32_16x16x128_f8f6f4 v[44:47], v[0:7], v[188:195], v[220:223]
	v_mfma_f32_16x16x128_f8f6f4 v[40:43], v[8:15], v[188:195], v[224:227]
	v_mfma_f32_16x16x128_f8f6f4 v[84:87], v[16:23], v[32:39], v[84:87]
	v_mfma_f32_16x16x128_f8f6f4 v[80:83], v[24:31], v[32:39], v[80:83]
	v_mfma_f32_16x16x128_f8f6f4 v[68:71], v[16:23], v[48:55], v[68:71]
	v_mfma_f32_16x16x128_f8f6f4 v[64:67], v[24:31], v[48:55], v[64:67]
	v_mfma_f32_16x16x128_f8f6f4 v[52:55], v[16:23], v[180:187], v[228:231]
	v_mfma_f32_16x16x128_f8f6f4 v[48:51], v[24:31], v[180:187], v[196:199]
	v_mfma_f32_16x16x128_f8f6f4 v[36:39], v[16:23], v[188:195], v[200:203]
	v_mfma_f32_16x16x128_f8f6f4 v[32:35], v[24:31], v[188:195], v[204:207]
	s_setprio 0
	s_barrier
	s_add_i32 s57, s57, 2
	s_cmp_gt_u32 s57, 5
	s_cbranch_scc1 .LBB0_1253
	s_mov_b64 s[22:23], s[24:25]
	s_branch .LBB0_1248

.LBB0_1316:
	s_add_u32 s8, s66, 0xf80000
	s_mov_b64 s[10:11], 0x80
	s_addc_u32 s9, s67, 0
	s_add_i32 m0, s25, 0x18000
	v_lshl_add_u64 v[4:5], v[4:5], 0, s[10:11]
	s_waitcnt vmcnt(2)
	s_barrier
	global_load_lds_dwordx4 v[4:5], off
	v_lshl_add_u64 v[2:3], v[2:3], 0, s[10:11]
	s_add_i32 m0, s25, 0x1a000
	s_add_i32 s36, s25, 0x8000
	s_add_i32 s37, s25, 0xa000
	global_load_lds_dwordx4 v[2:3], off
	v_lshl_add_u64 v[0:1], v[0:1], 0, s[10:11]
	s_mov_b32 m0, s36
	s_add_u32 s0, s18, 0x58080
	global_load_lds_dwordx4 v[0:1], off
	v_lshl_add_u64 v[0:1], v[6:7], 0, s[10:11]
	s_mov_b32 m0, s37
	s_addc_u32 s1, s19, 0
	global_load_lds_dwordx4 v[0:1], off
	s_add_i32 m0, s25, 0x1c000
	v_lshl_add_u64 v[0:1], s[0:1], 0, v[162:163]
	global_load_lds_dwordx4 v[0:1], off
	v_lshl_add_u64 v[0:1], s[0:1], 0, v[160:161]
	s_add_i32 m0, s25, 0x1e000
	v_and_b32_e32 v2, 48, v8
	global_load_lds_dwordx4 v[0:1], off
	v_and_b32_e32 v0, 15, v8
	v_or_b32_e32 v1, s91, v0
	v_lshlrev_b32_e32 v3, 6, v1
	s_movk_i32 s0, 0x3c0
	v_and_or_b32 v3, v3, s0, v2
	v_lshl_or_b32 v0, v0, 6, v2
	v_lshlrev_b32_e32 v2, 2, v8
	v_lshlrev_b32_e32 v1, 2, v1
	v_and_b32_e32 v2, 32, v2
	v_and_b32_e32 v1, 32, v1
	v_readlane_b32 s0, v253, 38
	v_bitop3_b32 v173, v0, s74, v2 bitop3:0xde
	s_waitcnt vmcnt(6)
	s_cmpk_lt_u32 s76, 0x100
	v_bitop3_b32 v1, v3, s0, v1 bitop3:0xde
	s_cselect_b64 s[12:13], -1, 0
	s_add_u32 s38, s66, 0x19400080
	v_add_u32_e32 v0, 0, v173
	s_mov_b32 s69, s5
	s_addc_u32 s39, s67, 0
	v_add_u32_e32 v175, 0x10000, v0
	v_add_u32_e32 v176, 0x14000, v0
	v_add_u32_e32 v177, 0, v1
	s_add_i32 s40, s25, 0xc000
	s_add_i32 s41, s25, 0xe000
	s_mov_b32 s42, 0
	s_barrier
	v_add_u32_e32 v247, s33, v174
	v_bfe_u32 v248, v247, 6, 1
	v_and_b32_e32 v249, 3, v247
	v_bfe_u32 v250, v247, 5, 1
	v_lshlrev_b32_e32 v249, 4, v249
	v_lshlrev_b32_e32 v250, 5, v250
	v_xor_b32_e32 v249, v249, v250
	v_lshl_add_u32 v248, v248, 6, v249
	v_lshrrev_b32_e32 v249, 7, v247
	v_bfe_u32 v247, v247, 2, 4
	v_lshl_add_u32 v247, v249, 4, v247
	v_mul_u32_u24_e32 v247, 0xb00, v247
	v_add_u32_e32 v247, v247, v248
	s_waitcnt vmcnt(0)
	s_branch .LBB0_1319

.LBB0_1323:
	s_lshl_b32 s48, s43, 8
	s_or_b32 s49, s48, 0x80
	s_add_u32 s50, s18, 0x100
	s_addc_u32 s51, s19, 0
	s_mov_b32 s52, -2
	s_mov_b64 s[18:19], 0
	ds_read_b128 v[16:19], v175
	ds_read_b128 v[20:23], v175 offset:1024
	ds_read_b128 v[24:27], v175 offset:2048
	ds_read_b128 v[28:31], v175 offset:3072
	ds_read_b128 v[0:3], v176
	ds_read_b128 v[4:7], v176 offset:1024
	ds_read_b128 v[8:11], v176 offset:2048
	ds_read_b128 v[12:15], v176 offset:3072
	s_cmp_eq_u32 s52, 18
	s_cselect_b64 s[22:23], -1, 0
	s_add_u32 s20, s38, s18
	s_addc_u32 s21, s39, s19
	s_mov_b32 m0, s40
	ds_read_b128 v[178:181], v177
	ds_read_b128 v[182:185], v177 offset:1024
	ds_read_b128 v[186:189], v177 offset:2048
	ds_read_b128 v[190:193], v177 offset:3072
	ds_read_b128 v[194:197], v177 offset:4096
	ds_read_b128 v[198:201], v177 offset:5120
	ds_read_b128 v[202:205], v177 offset:6144
	ds_read_b128 v[206:209], v177 offset:7168
	global_load_lds_dwordx4 v166, s[20:21]
	s_mov_b32 m0, s41
	s_nop 0
	global_load_lds_dwordx4 v170, s[20:21]
	s_waitcnt vmcnt(24)
	s_waitcnt lgkmcnt(0)
	s_barrier
	s_setprio 1
	s_waitcnt lgkmcnt(0)
	v_mfma_f32_16x16x128_f8f6f4 v[156:159], v[16:23], v[178:185], 0
	v_mfma_f32_16x16x128_f8f6f4 v[152:155], v[24:31], v[178:185], 0
	v_mfma_f32_16x16x128_f8f6f4 v[140:143], v[16:23], v[186:193], 0
	v_mfma_f32_16x16x128_f8f6f4 v[136:139], v[24:31], v[186:193], 0
	v_mfma_f32_16x16x128_f8f6f4 v[124:127], v[16:23], v[194:201], 0
	v_mfma_f32_16x16x128_f8f6f4 v[120:123], v[24:31], v[194:201], 0
	v_mfma_f32_16x16x128_f8f6f4 v[108:111], v[16:23], v[202:209], 0
	v_mfma_f32_16x16x128_f8f6f4 v[104:107], v[24:31], v[202:209], 0
	v_mfma_f32_16x16x128_f8f6f4 v[148:151], v[0:7], v[178:185], 0
	v_mfma_f32_16x16x128_f8f6f4 v[144:147], v[8:15], v[178:185], 0
	v_mfma_f32_16x16x128_f8f6f4 v[132:135], v[0:7], v[186:193], 0
	v_mfma_f32_16x16x128_f8f6f4 v[128:131], v[8:15], v[186:193], 0
	v_mfma_f32_16x16x128_f8f6f4 v[116:119], v[0:7], v[194:201], 0
	v_mfma_f32_16x16x128_f8f6f4 v[112:115], v[8:15], v[194:201], 0
	v_mfma_f32_16x16x128_f8f6f4 v[100:103], v[0:7], v[202:209], 0
	v_mfma_f32_16x16x128_f8f6f4 v[96:99], v[8:15], v[202:209], 0
	s_setprio 0
	s_barrier
	s_and_b64 s[20:21], s[16:17], s[22:23]
	s_andn2_b64 vcc, exec, s[20:21]
	s_cbranch_vccnz .Lpk3_LBB0_1326
	s_mul_i32 s57, s48, s28
	s_mul_i32 s58, s49, s28
	v_add_u32_e32 v164, s57, v247
	v_add_u32_e32 v166, s58, v247
	v_add_u32_e32 v168, 0x2c000, v164
	v_add_u32_e32 v170, 0x2c000, v166
	s_branch .Lpk3_LBB0_1327
.Lpk3_LBB0_1326:
.Lpk3_LBB0_1327:
	s_add_u32 s20, s18, 0x100
	s_addc_u32 s21, s19, 0
	s_and_b64 s[56:57], s[22:23], exec
	s_cselect_b32 s4, 0, s20
	s_add_u32 s53, s50, s18
	s_addc_u32 s56, s51, s19
	s_and_b64 s[18:19], s[22:23], exec
	s_cselect_b32 s19, s15, s56
	s_cselect_b32 s18, s14, s53
	s_add_u32 s98, s2, s4
	s_addc_u32 s99, s3, s5
	s_mov_b32 m0, s26
	s_add_u32 s22, s18, 0x58000
	ds_read_b128 v[178:181], v177 offset:16384
	ds_read_b128 v[182:185], v177 offset:17408
	ds_read_b128 v[186:189], v177 offset:18432
	ds_read_b128 v[190:193], v177 offset:19456
	ds_read_b128 v[194:197], v177 offset:20480
	ds_read_b128 v[198:201], v177 offset:21504
	ds_read_b128 v[202:205], v177 offset:22528
	ds_read_b128 v[206:209], v177 offset:23552
	global_load_lds_dwordx4 v162, s[18:19]
	s_mov_b32 m0, s27
	s_addc_u32 s23, s19, 0
	global_load_lds_dwordx4 v160, s[18:19]
	s_mov_b32 m0, s29
	s_nop 0
	global_load_lds_dwordx4 v162, s[22:23]
	s_mov_b32 m0, s30
	s_nop 0
	global_load_lds_dwordx4 v160, s[22:23]
	s_waitcnt vmcnt(22)
	s_waitcnt lgkmcnt(0)
	s_barrier
	s_setprio 1
	s_waitcnt lgkmcnt(0)
	v_mfma_f32_16x16x128_f8f6f4 v[92:95], v[16:23], v[178:185], 0
	v_mfma_f32_16x16x128_f8f6f4 v[88:91], v[24:31], v[178:185], 0
	v_mfma_f32_16x16x128_f8f6f4 v[76:79], v[16:23], v[186:193], 0
	v_mfma_f32_16x16x128_f8f6f4 v[72:75], v[24:31], v[186:193], 0
	v_mfma_f32_16x16x128_f8f6f4 v[210:213], v[16:23], v[194:201], 0
	v_mfma_f32_16x16x128_f8f6f4 v[214:217], v[24:31], v[194:201], 0
	v_mfma_f32_16x16x128_f8f6f4 v[218:221], v[16:23], v[202:209], 0
	v_mfma_f32_16x16x128_f8f6f4 v[222:225], v[24:31], v[202:209], 0
	v_mfma_f32_16x16x128_f8f6f4 v[84:87], v[0:7], v[178:185], 0
	v_mfma_f32_16x16x128_f8f6f4 v[80:83], v[8:15], v[178:185], 0
	v_mfma_f32_16x16x128_f8f6f4 v[68:71], v[0:7], v[186:193], 0
	v_mfma_f32_16x16x128_f8f6f4 v[64:67], v[8:15], v[186:193], 0
	v_mfma_f32_16x16x128_f8f6f4 v[226:229], v[0:7], v[194:201], 0
	v_mfma_f32_16x16x128_f8f6f4 v[194:197], v[8:15], v[194:201], 0
	v_mfma_f32_16x16x128_f8f6f4 v[198:201], v[0:7], v[202:209], 0
	v_mfma_f32_16x16x128_f8f6f4 v[202:205], v[8:15], v[202:209], 0
	s_setprio 0
	s_barrier
	s_add_i32 s22, 0, 0x18000
	s_add_i32 s23, 0, 0x1c000
	v_add_u32_e32 v12, s22, v173
	v_add_u32_e32 v28, s23, v173
	ds_read_b128 v[0:3], v12
	ds_read_b128 v[4:7], v12 offset:1024
	ds_read_b128 v[8:11], v12 offset:2048
	ds_read_b128 v[12:15], v12 offset:3072
	ds_read_b128 v[16:19], v28
	ds_read_b128 v[20:23], v28 offset:1024
	ds_read_b128 v[24:27], v28 offset:2048
	ds_read_b128 v[28:31], v28 offset:3072
	s_mov_b32 m0, s34
	ds_read_b128 v[32:35], v177 offset:32768
	ds_read_b128 v[36:39], v177 offset:33792
	ds_read_b128 v[40:43], v177 offset:34816
	ds_read_b128 v[44:47], v177 offset:35840
	ds_read_b128 v[48:51], v177 offset:36864
	ds_read_b128 v[52:55], v177 offset:37888
	ds_read_b128 v[56:59], v177 offset:38912
	ds_read_b128 v[60:63], v177 offset:39936
	global_load_lds_dwordx4 v166, s[98:99]
	s_mov_b32 m0, s35
	s_nop 0
	global_load_lds_dwordx4 v170, s[98:99]
	s_mov_b32 m0, s25
	s_nop 0
	global_load_lds_dwordx4 v164, s[98:99]
	s_mov_b32 m0, s31
	s_nop 0
	global_load_lds_dwordx4 v168, s[98:99]
	s_waitcnt vmcnt(8)
	s_waitcnt lgkmcnt(0)
	s_barrier
	s_setprio 1
	s_waitcnt lgkmcnt(0)
	v_mfma_f32_16x16x128_f8f6f4 v[156:159], v[0:7], v[32:39], v[156:159]
	v_mfma_f32_16x16x128_f8f6f4 v[152:155], v[8:15], v[32:39], v[152:155]
	v_mfma_f32_16x16x128_f8f6f4 v[140:143], v[0:7], v[40:47], v[140:143]
	v_mfma_f32_16x16x128_f8f6f4 v[136:139], v[8:15], v[40:47], v[136:139]
	v_mfma_f32_16x16x128_f8f6f4 v[124:127], v[0:7], v[48:55], v[124:127]
	v_mfma_f32_16x16x128_f8f6f4 v[120:123], v[8:15], v[48:55], v[120:123]
	v_mfma_f32_16x16x128_f8f6f4 v[108:111], v[0:7], v[56:63], v[108:111]
	v_mfma_f32_16x16x128_f8f6f4 v[104:107], v[8:15], v[56:63], v[104:107]
	v_mfma_f32_16x16x128_f8f6f4 v[148:151], v[16:23], v[32:39], v[148:151]
	v_mfma_f32_16x16x128_f8f6f4 v[144:147], v[24:31], v[32:39], v[144:147]
	v_mfma_f32_16x16x128_f8f6f4 v[132:135], v[16:23], v[40:47], v[132:135]
	v_mfma_f32_16x16x128_f8f6f4 v[128:131], v[24:31], v[40:47], v[128:131]
	v_mfma_f32_16x16x128_f8f6f4 v[116:119], v[16:23], v[48:55], v[116:119]
	v_mfma_f32_16x16x128_f8f6f4 v[112:115], v[24:31], v[48:55], v[112:115]
	v_mfma_f32_16x16x128_f8f6f4 v[100:103], v[16:23], v[56:63], v[100:103]
	v_mfma_f32_16x16x128_f8f6f4 v[96:99], v[24:31], v[56:63], v[96:99]
	s_setprio 0
	s_barrier
	s_add_i32 s4, s22, s84
	s_add_u32 s100, s18, s10
	s_addc_u32 s101, s19, s11
	s_add_u32 s98, s98, s10
	s_addc_u32 s99, s99, s11
	s_mov_b32 m0, s4
	ds_read_b128 v[32:35], v177 offset:49152
	ds_read_b128 v[36:39], v177 offset:50176
	ds_read_b128 v[48:51], v177 offset:51200
	ds_read_b128 v[52:55], v177 offset:52224
	ds_read_b128 v[178:181], v177 offset:53248
	ds_read_b128 v[182:185], v177 offset:54272
	ds_read_b128 v[186:189], v177 offset:55296
	ds_read_b128 v[190:193], v177 offset:56320
	global_load_lds_dwordx4 v162, s[100:101]
	s_add_i32 m0, s4, 0x2000
	s_add_u32 s18, s18, 0x58080
	s_addc_u32 s19, s19, 0
	s_add_i32 s4, s23, s84
	global_load_lds_dwordx4 v160, s[100:101]
	s_mov_b32 m0, s4
	s_nop 0
	global_load_lds_dwordx4 v162, s[18:19]
	s_add_i32 m0, s4, 0x2000
	s_nop 0
	global_load_lds_dwordx4 v160, s[18:19]
	s_mov_b32 m0, s36
	s_nop 0
	global_load_lds_dwordx4 v164, s[98:99]
	s_mov_b32 m0, s37
	s_nop 0
	global_load_lds_dwordx4 v168, s[98:99]
	s_waitcnt vmcnt(6)
	s_waitcnt lgkmcnt(0)
	s_barrier
	s_setprio 1
	s_waitcnt lgkmcnt(0)
	v_mfma_f32_16x16x128_f8f6f4 v[92:95], v[0:7], v[32:39], v[92:95]
	v_mfma_f32_16x16x128_f8f6f4 v[88:91], v[8:15], v[32:39], v[88:91]
	v_mfma_f32_16x16x128_f8f6f4 v[76:79], v[0:7], v[48:55], v[76:79]
	v_mfma_f32_16x16x128_f8f6f4 v[72:75], v[8:15], v[48:55], v[72:75]
	v_mfma_f32_16x16x128_f8f6f4 v[60:63], v[0:7], v[178:185], v[210:213]
	v_mfma_f32_16x16x128_f8f6f4 v[56:59], v[8:15], v[178:185], v[214:217]
	v_mfma_f32_16x16x128_f8f6f4 v[44:47], v[0:7], v[186:193], v[218:221]
	v_mfma_f32_16x16x128_f8f6f4 v[40:43], v[8:15], v[186:193], v[222:225]
	v_mfma_f32_16x16x128_f8f6f4 v[84:87], v[16:23], v[32:39], v[84:87]
	v_mfma_f32_16x16x128_f8f6f4 v[80:83], v[24:31], v[32:39], v[80:83]
	v_mfma_f32_16x16x128_f8f6f4 v[68:71], v[16:23], v[48:55], v[68:71]
	v_mfma_f32_16x16x128_f8f6f4 v[64:67], v[24:31], v[48:55], v[64:67]
	v_mfma_f32_16x16x128_f8f6f4 v[52:55], v[16:23], v[178:185], v[226:229]
	v_mfma_f32_16x16x128_f8f6f4 v[48:51], v[24:31], v[178:185], v[194:197]
	v_mfma_f32_16x16x128_f8f6f4 v[36:39], v[16:23], v[186:193], v[198:201]
	v_mfma_f32_16x16x128_f8f6f4 v[32:35], v[24:31], v[186:193], v[202:205]
	s_setprio 0
	s_barrier
	s_add_i32 s52, s52, 2
	s_cmp_gt_u32 s52, 19
	s_cbranch_scc1 .LBB0_1329
	s_mov_b64 s[18:19], s[20:21]
	s_branch .LBB0_1324
